# sample_out_unit: 32 GEMM loads up front, x loads hoisted, slot loads batched (2x32)
# speedup vs baseline: 1.0046x; 1.0039x over previous
.LBB0_626:
	v_lshl_add_u64 v[26:27], v[20:21], 0, v[16:17]
	v_add_co_u32_e32 v54, vcc, s6, v26
	v_lshl_add_u64 v[28:29], v[18:19], 0, v[16:17]
	s_nop 0
	v_addc_co_u32_e32 v55, vcc, 0, v27, vcc
	v_add_co_u32_e32 v56, vcc, s7, v26
	s_nop 1
	v_addc_co_u32_e32 v57, vcc, 0, v27, vcc
	v_add_co_u32_e32 v58, vcc, s8, v28
	s_nop 1
	v_addc_co_u32_e32 v59, vcc, 0, v29, vcc
	v_add_co_u32_e32 v60, vcc, s9, v28
	s_nop 1
	v_addc_co_u32_e32 v61, vcc, 0, v29, vcc
	v_and_b32_e32 v200, 31, v23
	v_ashrrev_i32_e32 v202, 5, v22
	v_or_b32_e32 v200, s4, v200
	v_ashrrev_i32_e32 v203, 31, v202
	v_ashrrev_i32_e32 v201, 31, v200
	v_lshlrev_b64 v[202:203], 13, v[202:203]
	v_lshl_add_u64 v[200:201], v[200:201], 2, s[46:47]
	v_lshl_add_u64 v[200:201], v[200:201], 0, v[202:203]
	global_load_dword v204, v[200:201], off
	v_add_co_u32_e32 v200, vcc, 0x20000, v200
	s_nop 1
	v_addc_co_u32_e32 v201, vcc, 0, v201, vcc
	global_load_dword v205, v[200:201], off
	global_load_dwordx4 v[64:67], v[54:55], off
	global_load_dwordx4 v[68:71], v[58:59], off
	global_load_dwordx4 v[72:75], v[60:61], off
	global_load_dwordx4 v[76:79], v[56:57], off
	global_load_dwordx4 v[80:83], v[54:55], off offset:64
	global_load_dwordx4 v[84:87], v[58:59], off offset:64
	global_load_dwordx4 v[88:91], v[60:61], off offset:64
	global_load_dwordx4 v[92:95], v[56:57], off offset:64
	global_load_dwordx4 v[96:99], v[54:55], off offset:128
	global_load_dwordx4 v[100:103], v[58:59], off offset:128
	global_load_dwordx4 v[104:107], v[60:61], off offset:128
	global_load_dwordx4 v[108:111], v[56:57], off offset:128
	global_load_dwordx4 v[112:115], v[54:55], off offset:192
	global_load_dwordx4 v[116:119], v[58:59], off offset:192
	global_load_dwordx4 v[120:123], v[60:61], off offset:192
	global_load_dwordx4 v[124:127], v[56:57], off offset:192
	global_load_dwordx4 v[128:131], v[54:55], off offset:256
	global_load_dwordx4 v[132:135], v[58:59], off offset:256
	global_load_dwordx4 v[136:139], v[60:61], off offset:256
	global_load_dwordx4 v[140:143], v[56:57], off offset:256
	global_load_dwordx4 v[144:147], v[54:55], off offset:320
	global_load_dwordx4 v[148:151], v[58:59], off offset:320
	global_load_dwordx4 v[152:155], v[60:61], off offset:320
	global_load_dwordx4 v[156:159], v[56:57], off offset:320
	global_load_dwordx4 v[160:163], v[54:55], off offset:384
	global_load_dwordx4 v[164:167], v[58:59], off offset:384
	global_load_dwordx4 v[192:195], v[60:61], off offset:384
	global_load_dwordx4 v[172:175], v[56:57], off offset:384
	global_load_dwordx4 v[176:179], v[54:55], off offset:448
	global_load_dwordx4 v[180:183], v[58:59], off offset:448
	global_load_dwordx4 v[184:187], v[60:61], off offset:448
	global_load_dwordx4 v[188:191], v[56:57], off offset:448
	s_waitcnt vmcnt(30)
	v_mfma_f32_16x16x32_bf16 v[0:3], v[64:67], v[68:71], v[0:3]
	s_waitcnt vmcnt(29)
	v_mfma_f32_16x16x32_bf16 v[8:11], v[64:67], v[72:75], v[8:11]
	s_waitcnt vmcnt(28)
	v_mfma_f32_16x16x32_bf16 v[4:7], v[76:79], v[68:71], v[4:7]
	v_mfma_f32_16x16x32_bf16 v[12:15], v[76:79], v[72:75], v[12:15]
	s_waitcnt vmcnt(26)
	v_mfma_f32_16x16x32_bf16 v[0:3], v[80:83], v[84:87], v[0:3]
	s_waitcnt vmcnt(25)
	v_mfma_f32_16x16x32_bf16 v[8:11], v[80:83], v[88:91], v[8:11]
	s_waitcnt vmcnt(24)
	v_mfma_f32_16x16x32_bf16 v[4:7], v[92:95], v[84:87], v[4:7]
	v_mfma_f32_16x16x32_bf16 v[12:15], v[92:95], v[88:91], v[12:15]
	s_waitcnt vmcnt(22)
	v_mfma_f32_16x16x32_bf16 v[0:3], v[96:99], v[100:103], v[0:3]
	s_waitcnt vmcnt(21)
	v_mfma_f32_16x16x32_bf16 v[8:11], v[96:99], v[104:107], v[8:11]
	s_waitcnt vmcnt(20)
	v_mfma_f32_16x16x32_bf16 v[4:7], v[108:111], v[100:103], v[4:7]
	v_mfma_f32_16x16x32_bf16 v[12:15], v[108:111], v[104:107], v[12:15]
	s_waitcnt vmcnt(18)
	v_mfma_f32_16x16x32_bf16 v[0:3], v[112:115], v[116:119], v[0:3]
	s_waitcnt vmcnt(17)
	v_mfma_f32_16x16x32_bf16 v[8:11], v[112:115], v[120:123], v[8:11]
	s_waitcnt vmcnt(16)
	v_mfma_f32_16x16x32_bf16 v[4:7], v[124:127], v[116:119], v[4:7]
	v_mfma_f32_16x16x32_bf16 v[12:15], v[124:127], v[120:123], v[12:15]
	s_waitcnt vmcnt(14)
	v_mfma_f32_16x16x32_bf16 v[0:3], v[128:131], v[132:135], v[0:3]
	s_waitcnt vmcnt(13)
	v_mfma_f32_16x16x32_bf16 v[8:11], v[128:131], v[136:139], v[8:11]
	s_waitcnt vmcnt(12)
	v_mfma_f32_16x16x32_bf16 v[4:7], v[140:143], v[132:135], v[4:7]
	v_mfma_f32_16x16x32_bf16 v[12:15], v[140:143], v[136:139], v[12:15]
	s_waitcnt vmcnt(10)
	v_mfma_f32_16x16x32_bf16 v[0:3], v[144:147], v[148:151], v[0:3]
	s_waitcnt vmcnt(9)
	v_mfma_f32_16x16x32_bf16 v[8:11], v[144:147], v[152:155], v[8:11]
	s_waitcnt vmcnt(8)
	v_mfma_f32_16x16x32_bf16 v[4:7], v[156:159], v[148:151], v[4:7]
	v_mfma_f32_16x16x32_bf16 v[12:15], v[156:159], v[152:155], v[12:15]
	s_waitcnt vmcnt(6)
	v_mfma_f32_16x16x32_bf16 v[0:3], v[160:163], v[164:167], v[0:3]
	s_waitcnt vmcnt(5)
	v_mfma_f32_16x16x32_bf16 v[8:11], v[160:163], v[192:195], v[8:11]
	s_waitcnt vmcnt(4)
	v_mfma_f32_16x16x32_bf16 v[4:7], v[172:175], v[164:167], v[4:7]
	v_mfma_f32_16x16x32_bf16 v[12:15], v[172:175], v[192:195], v[12:15]
	s_waitcnt vmcnt(2)
	v_mfma_f32_16x16x32_bf16 v[0:3], v[176:179], v[180:183], v[0:3]
	s_waitcnt vmcnt(1)
	v_mfma_f32_16x16x32_bf16 v[8:11], v[176:179], v[184:187], v[8:11]
	s_waitcnt vmcnt(0)
	v_mfma_f32_16x16x32_bf16 v[4:7], v[188:191], v[180:183], v[4:7]
	v_mfma_f32_16x16x32_bf16 v[12:15], v[188:191], v[184:187], v[12:15]
	v_lshlrev_b32_e32 v16, 5, v23
	v_and_b32_e32 v16, 0x600, v16
	v_lshl_add_u32 v17, v24, 12, 0
	v_lshlrev_b32_e32 v18, 2, v25
	v_add3_u32 v16, v17, v18, v16
	ds_write2_b32 v16, v0, v8 offset1:16
	ds_write2_b32 v16, v1, v9 offset0:32 offset1:48
	ds_write2_b32 v16, v2, v10 offset0:64 offset1:80
	ds_write2_b32 v16, v3, v11 offset0:96 offset1:112
	v_add_u32_e32 v0, 0x800, v16
	v_and_b32_e32 v18, 31, v23
	ds_write2_b32 v0, v4, v12 offset1:16
	ds_write2_b32 v0, v5, v13 offset0:32 offset1:48
	ds_write2_b32 v0, v6, v14 offset0:64 offset1:80
	ds_write2_b32 v0, v7, v15 offset0:96 offset1:112
	v_or_b32_e32 v0, s4, v18
	v_ashrrev_i32_e32 v4, 5, v22
	v_ashrrev_i32_e32 v1, 31, v0
	v_ashrrev_i32_e32 v5, 31, v4
	v_lshl_add_u64 v[10:11], v[0:1], 2, s[46:47]
	v_lshlrev_b64 v[2:3], 13, v[4:5]
	v_lshl_add_u64 v[6:7], v[10:11], 0, v[2:3]
	s_waitcnt lgkmcnt(0)
	s_barrier
	v_mbcnt_hi_u32_b32 v19, -1, v169
	v_and_b32_e32 v6, 64, v19
	v_xor_b32_e32 v7, 1, v19
	v_add_u32_e32 v20, 64, v6
	v_lshl_add_u32 v12, v22, 2, 0
	v_cmp_lt_i32_e32 vcc, v7, v20
	s_lshl_b64 s[0:1], s[2:3], 2
	s_add_u32 s0, s92, s0
	v_cndmask_b32_e32 v13, v19, v7, vcc
	ds_read2st64_b32 v[6:7], v12 offset1:16
	ds_read2st64_b32 v[8:9], v12 offset0:32 offset1:48
	ds_read2st64_b32 v[14:15], v12 offset0:64 offset1:80
	ds_read2st64_b32 v[16:17], v12 offset0:96 offset1:112
	v_lshlrev_b32_e32 v13, 2, v13
	s_waitcnt lgkmcnt(3)
	v_add_f32_e32 v6, 0, v6
	v_add_f32_e32 v6, v6, v7
	s_waitcnt lgkmcnt(2)
	v_add_f32_e32 v6, v6, v8
	v_add_f32_e32 v6, v6, v9
	s_waitcnt lgkmcnt(1)
	v_add_f32_e32 v6, v6, v14
	v_add_f32_e32 v6, v6, v15
	s_waitcnt lgkmcnt(0)
	v_add_f32_e32 v6, v6, v16
	v_add_f32_e32 v6, v6, v17
	v_xor_b32_e32 v7, 2, v19
	v_cmp_lt_i32_e32 vcc, v7, v20
	v_xor_b32_e32 v8, 4, v19
	s_addc_u32 s1, s93, s1
	v_cndmask_b32_e32 v7, v19, v7, vcc
	v_lshlrev_b32_e32 v14, 2, v7
	v_cmp_lt_i32_e32 vcc, v8, v20
	s_add_u32 s0, s0, 0x140000
	s_addc_u32 s1, s1, 0
	v_cndmask_b32_e32 v8, v19, v8, vcc
	v_lshlrev_b32_e32 v15, 2, v8
	v_xor_b32_e32 v8, 8, v19
	v_cmp_lt_i32_e32 vcc, v8, v20
	s_waitcnt vmcnt(0)
	v_add_f32_e32 v5, v6, v204
	v_mul_f32_e32 v6, v5, v5
	ds_bpermute_b32 v6, v13, v6
	v_cndmask_b32_e32 v8, v19, v8, vcc
	v_lshlrev_b32_e32 v16, 2, v8
	v_xor_b32_e32 v8, 16, v19
	v_cmp_lt_i32_e32 vcc, v8, v20
	s_waitcnt lgkmcnt(0)
	v_fmac_f32_e32 v6, v5, v5
	ds_bpermute_b32 v7, v14, v6
	v_cndmask_b32_e32 v8, v19, v8, vcc
	v_lshlrev_b32_e32 v17, 2, v8
	v_cmp_eq_u32_e32 vcc, 0, v18
	s_waitcnt lgkmcnt(0)
	v_add_f32_e32 v6, v6, v7
	ds_bpermute_b32 v7, v15, v6
	s_waitcnt lgkmcnt(0)
	v_add_f32_e32 v6, v6, v7
	ds_bpermute_b32 v7, v16, v6
	s_waitcnt lgkmcnt(0)
	v_add_f32_e32 v6, v6, v7
	ds_bpermute_b32 v7, v17, v6
	s_and_saveexec_b64 s[4:5], vcc
	s_cbranch_execz .LBB0_629
	v_lshlrev_b32_e32 v8, 6, v4
	v_ashrrev_i32_e32 v9, 31, v8
	v_lshl_add_u64 v[8:9], v[8:9], 2, s[0:1]
	s_waitcnt lgkmcnt(0)
	v_add_f32_e32 v6, v6, v7
	global_store_dword v[8:9], v6, off sc1
.LBB0_629:
	s_or_b64 exec, exec, s[4:5]
	v_add_u32_e32 v6, 0x200, v22
	v_ashrrev_i32_e32 v8, 5, v6
	v_ashrrev_i32_e32 v9, 31, v8
	s_waitcnt lgkmcnt(0)
	v_lshlrev_b64 v[6:7], 13, v[8:9]
	v_lshl_add_u64 v[10:11], v[10:11], 0, v[6:7]
	ds_read2st64_b32 v[10:11], v12 offset0:8 offset1:24
	ds_read2st64_b32 v[18:19], v12 offset0:40 offset1:56
	ds_read2st64_b32 v[20:21], v12 offset0:72 offset1:88
	s_waitcnt lgkmcnt(2)
	v_add_f32_e32 v10, 0, v10
	v_add_f32_e32 v24, v10, v11
	ds_read2st64_b32 v[10:11], v12 offset0:104 offset1:120
	s_waitcnt lgkmcnt(2)
	v_add_f32_e32 v12, v24, v18
	v_add_f32_e32 v12, v12, v19
	s_waitcnt lgkmcnt(1)
	v_add_f32_e32 v12, v12, v20
	v_add_f32_e32 v12, v12, v21
	s_waitcnt lgkmcnt(0)
	v_add_f32_e32 v10, v12, v10
	v_add_f32_e32 v10, v10, v11
	s_waitcnt vmcnt(0)
	v_add_f32_e32 v9, v10, v205
	v_mul_f32_e32 v10, v9, v9
	ds_bpermute_b32 v10, v13, v10
	s_waitcnt lgkmcnt(0)
	v_fmac_f32_e32 v10, v9, v9
	ds_bpermute_b32 v11, v14, v10
	s_waitcnt lgkmcnt(0)
	v_add_f32_e32 v10, v10, v11
	ds_bpermute_b32 v11, v15, v10
	s_waitcnt lgkmcnt(0)
	v_add_f32_e32 v10, v10, v11
	ds_bpermute_b32 v11, v16, v10
	s_waitcnt lgkmcnt(0)
	v_add_f32_e32 v10, v10, v11
	ds_bpermute_b32 v11, v17, v10
	s_and_saveexec_b64 s[4:5], vcc
	s_cbranch_execz .LBB0_631
	v_lshlrev_b32_e32 v12, 6, v8
	v_ashrrev_i32_e32 v13, 31, v12
	v_lshl_add_u64 v[12:13], v[12:13], 2, s[0:1]
	s_waitcnt lgkmcnt(0)
	v_add_f32_e32 v10, v10, v11
	global_store_dword v[12:13], v10, off sc1

.LBB0_645:
	v_add_co_u32_e32 v16, vcc, 0x140000, v12
	s_nop 1
	v_addc_co_u32_e32 v17, vcc, 0, v13, vcc
	global_load_dword v64, v[16:17], off sc1
	global_load_dword v65, v[16:17], off offset:4 sc1
	global_load_dword v66, v[16:17], off offset:8 sc1
	global_load_dword v67, v[16:17], off offset:12 sc1
	global_load_dword v68, v[16:17], off offset:16 sc1
	global_load_dword v69, v[16:17], off offset:20 sc1
	global_load_dword v70, v[16:17], off offset:24 sc1
	global_load_dword v71, v[16:17], off offset:28 sc1
	global_load_dword v72, v[16:17], off offset:32 sc1
	global_load_dword v73, v[16:17], off offset:36 sc1
	global_load_dword v74, v[16:17], off offset:40 sc1
	global_load_dword v75, v[16:17], off offset:44 sc1
	global_load_dword v76, v[16:17], off offset:48 sc1
	global_load_dword v77, v[16:17], off offset:52 sc1
	global_load_dword v78, v[16:17], off offset:56 sc1
	global_load_dword v79, v[16:17], off offset:60 sc1
	global_load_dword v80, v[16:17], off offset:64 sc1
	global_load_dword v81, v[16:17], off offset:68 sc1
	global_load_dword v82, v[16:17], off offset:72 sc1
	global_load_dword v83, v[16:17], off offset:76 sc1
	global_load_dword v84, v[16:17], off offset:80 sc1
	global_load_dword v85, v[16:17], off offset:84 sc1
	global_load_dword v86, v[16:17], off offset:88 sc1
	global_load_dword v87, v[16:17], off offset:92 sc1
	global_load_dword v88, v[16:17], off offset:96 sc1
	global_load_dword v89, v[16:17], off offset:100 sc1
	global_load_dword v90, v[16:17], off offset:104 sc1
	global_load_dword v91, v[16:17], off offset:108 sc1
	global_load_dword v92, v[16:17], off offset:112 sc1
	global_load_dword v93, v[16:17], off offset:116 sc1
	global_load_dword v94, v[16:17], off offset:120 sc1
	global_load_dword v95, v[16:17], off offset:124 sc1
	s_waitcnt vmcnt(31)
	v_add_f32_e32 v10, v11, v64
	s_waitcnt vmcnt(30)
	v_add_f32_e32 v10, v10, v65
	s_waitcnt vmcnt(29)
	v_add_f32_e32 v10, v10, v66
	s_waitcnt vmcnt(28)
	v_add_f32_e32 v10, v10, v67
	s_waitcnt vmcnt(27)
	v_add_f32_e32 v10, v10, v68
	s_waitcnt vmcnt(26)
	v_add_f32_e32 v10, v10, v69
	s_waitcnt vmcnt(25)
	v_add_f32_e32 v10, v10, v70
	s_waitcnt vmcnt(24)
	v_add_f32_e32 v10, v10, v71
	s_waitcnt vmcnt(23)
	v_add_f32_e32 v10, v10, v72
	s_waitcnt vmcnt(22)
	v_add_f32_e32 v10, v10, v73
	s_waitcnt vmcnt(21)
	v_add_f32_e32 v10, v10, v74
	s_waitcnt vmcnt(20)
	v_add_f32_e32 v10, v10, v75
	s_waitcnt vmcnt(19)
	v_add_f32_e32 v10, v10, v76
	s_waitcnt vmcnt(18)
	v_add_f32_e32 v10, v10, v77
	s_waitcnt vmcnt(17)
	v_add_f32_e32 v10, v10, v78
	s_waitcnt vmcnt(16)
	v_add_f32_e32 v10, v10, v79
	s_waitcnt vmcnt(15)
	v_add_f32_e32 v10, v10, v80
	s_waitcnt vmcnt(14)
	v_add_f32_e32 v10, v10, v81
	s_waitcnt vmcnt(13)
	v_add_f32_e32 v10, v10, v82
	s_waitcnt vmcnt(12)
	v_add_f32_e32 v10, v10, v83
	s_waitcnt vmcnt(11)
	v_add_f32_e32 v10, v10, v84
	s_waitcnt vmcnt(10)
	v_add_f32_e32 v10, v10, v85
	s_waitcnt vmcnt(9)
	v_add_f32_e32 v10, v10, v86
	s_waitcnt vmcnt(8)
	v_add_f32_e32 v10, v10, v87
	s_waitcnt vmcnt(7)
	v_add_f32_e32 v10, v10, v88
	s_waitcnt vmcnt(6)
	v_add_f32_e32 v10, v10, v89
	s_waitcnt vmcnt(5)
	v_add_f32_e32 v10, v10, v90
	s_waitcnt vmcnt(4)
	v_add_f32_e32 v10, v10, v91
	s_waitcnt vmcnt(3)
	v_add_f32_e32 v10, v10, v92
	s_waitcnt vmcnt(2)
	v_add_f32_e32 v10, v10, v93
	s_waitcnt vmcnt(1)
	v_add_f32_e32 v10, v10, v94
	s_waitcnt vmcnt(0)
	v_add_f32_e32 v10, v10, v95
	global_load_dword v64, v[16:17], off offset:128 sc1
	global_load_dword v65, v[16:17], off offset:132 sc1
	global_load_dword v66, v[16:17], off offset:136 sc1
	global_load_dword v67, v[16:17], off offset:140 sc1
	global_load_dword v68, v[16:17], off offset:144 sc1
	global_load_dword v69, v[16:17], off offset:148 sc1
	global_load_dword v70, v[16:17], off offset:152 sc1
	global_load_dword v71, v[16:17], off offset:156 sc1
	global_load_dword v72, v[16:17], off offset:160 sc1
	global_load_dword v73, v[16:17], off offset:164 sc1
	global_load_dword v74, v[16:17], off offset:168 sc1
	global_load_dword v75, v[16:17], off offset:172 sc1
	global_load_dword v76, v[16:17], off offset:176 sc1
	global_load_dword v77, v[16:17], off offset:180 sc1
	global_load_dword v78, v[16:17], off offset:184 sc1
	global_load_dword v79, v[16:17], off offset:188 sc1
	global_load_dword v80, v[16:17], off offset:192 sc1
	global_load_dword v81, v[16:17], off offset:196 sc1
	global_load_dword v82, v[16:17], off offset:200 sc1
	global_load_dword v83, v[16:17], off offset:204 sc1
	global_load_dword v84, v[16:17], off offset:208 sc1
	global_load_dword v85, v[16:17], off offset:212 sc1
	global_load_dword v86, v[16:17], off offset:216 sc1
	global_load_dword v87, v[16:17], off offset:220 sc1
	global_load_dword v88, v[16:17], off offset:224 sc1
	global_load_dword v89, v[16:17], off offset:228 sc1
	global_load_dword v90, v[16:17], off offset:232 sc1
	global_load_dword v91, v[16:17], off offset:236 sc1
	global_load_dword v92, v[16:17], off offset:240 sc1
	global_load_dword v93, v[16:17], off offset:244 sc1
	global_load_dword v94, v[16:17], off offset:248 sc1
	global_load_dword v95, v[16:17], off offset:252 sc1
	s_waitcnt vmcnt(31)
	v_add_f32_e32 v10, v10, v64
	s_waitcnt vmcnt(30)
	v_add_f32_e32 v10, v10, v65
	s_waitcnt vmcnt(29)
	v_add_f32_e32 v10, v10, v66
	s_waitcnt vmcnt(28)
	v_add_f32_e32 v10, v10, v67
	s_waitcnt vmcnt(27)
	v_add_f32_e32 v10, v10, v68
	s_waitcnt vmcnt(26)
	v_add_f32_e32 v10, v10, v69
	s_waitcnt vmcnt(25)
	v_add_f32_e32 v10, v10, v70
	s_waitcnt vmcnt(24)
	v_add_f32_e32 v10, v10, v71
	s_waitcnt vmcnt(23)
	v_add_f32_e32 v10, v10, v72
	s_waitcnt vmcnt(22)
	v_add_f32_e32 v10, v10, v73
	s_waitcnt vmcnt(21)
	v_add_f32_e32 v10, v10, v74
	s_waitcnt vmcnt(20)
	v_add_f32_e32 v10, v10, v75
	s_waitcnt vmcnt(19)
	v_add_f32_e32 v10, v10, v76
	s_waitcnt vmcnt(18)
	v_add_f32_e32 v10, v10, v77
	s_waitcnt vmcnt(17)
	v_add_f32_e32 v10, v10, v78
	s_waitcnt vmcnt(16)
	v_add_f32_e32 v10, v10, v79
	s_waitcnt vmcnt(15)
	v_add_f32_e32 v10, v10, v80
	s_waitcnt vmcnt(14)
	v_add_f32_e32 v10, v10, v81
	s_waitcnt vmcnt(13)
	v_add_f32_e32 v10, v10, v82
	s_waitcnt vmcnt(12)
	v_add_f32_e32 v10, v10, v83
	s_waitcnt vmcnt(11)
	v_add_f32_e32 v10, v10, v84
	s_waitcnt vmcnt(10)
	v_add_f32_e32 v10, v10, v85
	s_waitcnt vmcnt(9)
	v_add_f32_e32 v10, v10, v86
	s_waitcnt vmcnt(8)
	v_add_f32_e32 v10, v10, v87
	s_waitcnt vmcnt(7)
	v_add_f32_e32 v10, v10, v88
	s_waitcnt vmcnt(6)
	v_add_f32_e32 v10, v10, v89
	s_waitcnt vmcnt(5)
	v_add_f32_e32 v10, v10, v90
	s_waitcnt vmcnt(4)
	v_add_f32_e32 v10, v10, v91
	s_waitcnt vmcnt(3)
	v_add_f32_e32 v10, v10, v92
	s_waitcnt vmcnt(2)
	v_add_f32_e32 v10, v10, v93
	s_waitcnt vmcnt(1)
	v_add_f32_e32 v10, v10, v94
	s_waitcnt vmcnt(0)
	v_add_f32_e32 v11, v10, v95
	v_mov_b32_e32 v10, 0x358637bd
	v_fmac_f32_e32 v10, 0x3a000000, v11
	s_mov_b32 s0, 0xf800000
	v_mul_f32_e32 v11, 0x4f800000, v10
	v_cmp_gt_f32_e32 vcc, s0, v10
	s_nop 1
	v_cndmask_b32_e32 v10, v10, v11, vcc
	v_sqrt_f32_e32 v11, v10
	s_nop 0
	v_add_u32_e32 v12, -1, v11
	v_fma_f32 v13, -v12, v11, v10
	v_cmp_ge_f32_e64 s[0:1], 0, v13
	v_add_u32_e32 v13, 1, v11
	s_nop 0
	v_cndmask_b32_e64 v12, v11, v12, s[0:1]
	v_fma_f32 v11, -v13, v11, v10
	v_cmp_lt_f32_e64 s[0:1], 0, v11
	s_nop 1
	v_cndmask_b32_e64 v11, v12, v13, s[0:1]
	v_mul_f32_e32 v12, 0x37800000, v11
	v_cndmask_b32_e32 v11, v11, v12, vcc
	v_mov_b32_e32 v12, 0x260
	v_cmp_class_f32_e32 vcc, v10, v12
	s_nop 1
	v_cndmask_b32_e32 v10, v11, v10, vcc
	v_div_scale_f32 v11, s[0:1], v10, v10, 1.0
	v_rcp_f32_e32 v12, v11
	s_nop 0
	v_fma_f32 v13, -v11, v12, 1.0
	v_fmac_f32_e32 v12, v13, v12
	v_div_scale_f32 v13, vcc, 1.0, v10, 1.0
	v_mul_f32_e32 v15, v13, v12
	v_fma_f32 v16, -v11, v15, v13
	v_fmac_f32_e32 v15, v16, v12
	v_fma_f32 v11, -v11, v15, v13
	v_div_fmas_f32 v11, v11, v12, v15
	v_div_fixup_f32 v10, v11, v10, 1.0
	v_lshl_add_u32 v11, v14, 2, 0
	ds_write_b32 v11, v10 offset:32768
